# hand-scheduled SwiGLU epilogue (staged exp/rcp, rs^2 folded into the reciprocal, cheaper u64 to f32 row-stat conversion, running store address) on top of v31
# baseline (speedup 1.0000x reference)
; __device__ __forceinline__ unsigned cvt_pk_bf16(float lo, float hi) { unsigned r; asm volatile("v_cvt_pk_bf16_f32 %0, %1, %2" : "=v"(r) : "v"(lo), "v"(hi)); return r; }
; __device__ __forceinline__ float ld_agent(const rss_t* p) { return (float)__hip_atomic_load(p, __ATOMIC_RELAXED, __HIP_MEMORY_SCOPE_AGENT) * (1.0f / 16777216.0f); }
; __device__ __forceinline__ rss_t rss_fix(float ss) { return (rss_t)(ss * 16777216.0f); }
; __device__ __forceinline__ float rstd_of(const rss_t* rowss, int row) { return __builtin_amdgcn_rsqf(ld_agent(rowss + row) * (1.0f / 1024.0f) + 1e-6f); }
; __device__ __forceinline__ unsigned silu_pk(f32x2 g, f32x2 u, float k1, float k2) {
;     const f32x2 t = g * k1; f32x2 ex; ex.x = __builtin_amdgcn_exp2f(t.x); ex.y = __builtin_amdgcn_exp2f(t.y);
;     const f32x2 d = ex + 1.0f; f32x2 r; r.x = __builtin_amdgcn_rcpf(d.x); r.y = __builtin_amdgcn_rcpf(d.y);
;     const f32x2 o = (g * u) * (r * k2);
;     return cvt_pk_bf16(o.x, o.y);
;     __device__ __forceinline__ void operator()(const f32x4 (&acc)[2][2][4][2], const Unit& u, int wr, int wc, int fr, int fq) const {
;         const int row0 = u.pm * BM + wr * 64 + fr, col0 = u.pn * HALF + wc * 32 + 8 * fq;
;         float ssq[2][4];
; #pragma unroll
;         for (int ai = 0; ai < 2; ++ai)
; #pragma unroll
;             for (int m = 0; m < 4; ++m) ssq[ai][m] = ld_agent(rowss + row0 + ai * HALF + m * 16);
; #pragma unroll
;         for (int ai = 0; ai < 2; ++ai)
; #pragma unroll
;             for (int m = 0; m < 4; ++m) {
;                 const int row = row0 + ai * HALF + m * 16; const float rs = __builtin_amdgcn_rsqf(ssq[ai][m] * (1.0f / 1024.0f) + 1e-6f);
;                 const float k1 = -1.4426950408889634f * rs, k2 = rs * rs;
;                 u32x4 w;
; #pragma unroll
;                 for (int n = 0; n < 2; ++n) {
;                     const f32x4 gv = acc[ai][0][m][n], uv = acc[ai][1][m][n];
;                     const unsigned lo = silu_pk((f32x2){gv[0], gv[1]}, (f32x2){uv[0], uv[1]}, k1, k2), hi = silu_pk((f32x2){gv[2], gv[3]}, (f32x2){uv[2], uv[3]}, k1, k2);
;                     if (n == 0) { w.x = lo; w.y = hi; } else { w.z = lo; w.w = hi; }
;                 }
;                 *(u32x4*)(O + (size_t)row * ldc + col0) = w;
.LBB0_235:
	v_lshl_add_u32 v144, s36, 8, v146
	v_ashrrev_i32_e32 v145, 31, v144
	v_lshl_add_u64 v[154:155], v[144:145], 3, s[8:9]
	global_load_dwordx2 v[156:157], v[154:155], off sc1
	global_load_dwordx2 v[158:159], v[154:155], off offset:128 sc1
	global_load_dwordx2 v[160:161], v[154:155], off offset:256 sc1
	global_load_dwordx2 v[162:163], v[154:155], off offset:384 sc1
	global_load_dwordx2 v[164:165], v[154:155], off offset:1024 sc1
	global_load_dwordx2 v[166:167], v[154:155], off offset:1152 sc1
	global_load_dwordx2 v[168:169], v[154:155], off offset:1280 sc1
	global_load_dwordx2 v[170:171], v[154:155], off offset:1408 sc1
	v_pk_mul_f32 v[124:125], v[120:121], v[124:125]
	v_pk_mul_f32 v[126:127], v[122:123], v[126:127]
	v_pk_mul_f32 v[112:113], v[116:117], v[112:113]
	v_pk_mul_f32 v[114:115], v[118:119], v[114:115]
	v_pk_mul_f32 v[104:105], v[108:109], v[104:105]
	v_pk_mul_f32 v[106:107], v[110:111], v[106:107]
	v_pk_mul_f32 v[96:97], v[100:101], v[96:97]
	v_pk_mul_f32 v[98:99], v[102:103], v[98:99]
	v_pk_mul_f32 v[88:89], v[92:93], v[88:89]
	v_pk_mul_f32 v[90:91], v[94:95], v[90:91]
	v_pk_mul_f32 v[80:81], v[84:85], v[80:81]
	v_pk_mul_f32 v[82:83], v[86:87], v[82:83]
	v_pk_mul_f32 v[72:73], v[76:77], v[72:73]
	v_pk_mul_f32 v[74:75], v[78:79], v[74:75]
	v_pk_mul_f32 v[64:65], v[68:69], v[64:65]
	v_pk_mul_f32 v[66:67], v[70:71], v[66:67]
	v_pk_mul_f32 v[56:57], v[60:61], v[56:57]
	v_pk_mul_f32 v[58:59], v[62:63], v[58:59]
	v_pk_mul_f32 v[48:49], v[52:53], v[48:49]
	v_pk_mul_f32 v[50:51], v[54:55], v[50:51]
	v_pk_mul_f32 v[40:41], v[44:45], v[40:41]
	v_pk_mul_f32 v[42:43], v[46:47], v[42:43]
	v_pk_mul_f32 v[32:33], v[36:37], v[32:33]
	v_pk_mul_f32 v[34:35], v[38:39], v[34:35]
	v_pk_mul_f32 v[24:25], v[28:29], v[24:25]
	v_pk_mul_f32 v[26:27], v[30:31], v[26:27]
	v_pk_mul_f32 v[16:17], v[20:21], v[16:17]
	v_pk_mul_f32 v[18:19], v[22:23], v[18:19]
	v_pk_mul_f32 v[8:9], v[12:13], v[8:9]
	v_pk_mul_f32 v[10:11], v[14:15], v[10:11]
	v_pk_mul_f32 v[0:1], v[4:5], v[0:1]
	v_pk_mul_f32 v[2:3], v[6:7], v[2:3]
	v_lshl_or_b32 v222, s63, 7, v148
	v_ashrrev_i32_e32 v223, 31, v222
	v_mov_b64_e32 v[224:225], s[12:13]
	v_lshlrev_b64 v[222:223], 1, v[222:223]
	v_mad_i64_i32 v[220:221], s[38:39], v144, s59, v[224:225]
	s_mov_b64 s[96:97], 0x16000
	s_mov_b64 s[98:99], 0x6e000
	v_lshl_add_u64 v[220:221], v[220:221], 0, v[222:223]
	s_waitcnt vmcnt(0)
	v_cvt_f32_u32_e32 v188, v157
	v_cvt_f32_u32_e32 v190, v159
	v_cvt_f32_u32_e32 v192, v161
	v_cvt_f32_u32_e32 v194, v163
	v_cvt_f32_u32_e32 v196, v165
	v_cvt_f32_u32_e32 v198, v167
	v_cvt_f32_u32_e32 v200, v169
	v_cvt_f32_u32_e32 v202, v171
	v_cvt_f32_u32_e32 v189, v156
	v_cvt_f32_u32_e32 v191, v158
	v_cvt_f32_u32_e32 v193, v160
	v_cvt_f32_u32_e32 v195, v162
	v_cvt_f32_u32_e32 v197, v164
	v_cvt_f32_u32_e32 v199, v166
	v_cvt_f32_u32_e32 v201, v168
	v_cvt_f32_u32_e32 v203, v170
	v_fmamk_f32 v188, v188, 0x4f800000, v189
	v_fmamk_f32 v190, v190, 0x4f800000, v191
	v_fmamk_f32 v192, v192, 0x4f800000, v193
	v_fmamk_f32 v194, v194, 0x4f800000, v195
	v_fmamk_f32 v196, v196, 0x4f800000, v197
	v_fmamk_f32 v198, v198, 0x4f800000, v199
	v_fmamk_f32 v200, v200, 0x4f800000, v201
	v_fmamk_f32 v202, v202, 0x4f800000, v203
	v_fmamk_f32 v173, v188, 0x2e800000, v152
	v_fmamk_f32 v175, v190, 0x2e800000, v152
	v_fmamk_f32 v177, v192, 0x2e800000, v152
	v_fmamk_f32 v179, v194, 0x2e800000, v152
	v_fmamk_f32 v181, v196, 0x2e800000, v152
	v_fmamk_f32 v183, v198, 0x2e800000, v152
	v_fmamk_f32 v185, v200, 0x2e800000, v152
	v_fmamk_f32 v187, v202, 0x2e800000, v152
	v_rsq_f32_e32 v172, v173
	v_rsq_f32_e32 v174, v175
	v_rsq_f32_e32 v176, v177
	v_rsq_f32_e32 v178, v179
	v_rsq_f32_e32 v180, v181
	v_rsq_f32_e32 v182, v183
	v_rsq_f32_e32 v184, v185
	v_rsq_f32_e32 v186, v187
	v_mul_f32_e32 v172, 0xbfb8aa3b, v172
	v_mul_f32_e32 v174, 0xbfb8aa3b, v174
	v_mul_f32_e32 v176, 0xbfb8aa3b, v176
	v_mul_f32_e32 v178, 0xbfb8aa3b, v178
	v_mul_f32_e32 v180, 0xbfb8aa3b, v180
	v_mul_f32_e32 v182, 0xbfb8aa3b, v182
	v_mul_f32_e32 v184, 0xbfb8aa3b, v184
	v_mul_f32_e32 v186, 0xbfb8aa3b, v186
	v_pk_mul_f32 v[188:189], v[120:121], v[172:173] op_sel_hi:[1,0]
	v_pk_mul_f32 v[190:191], v[122:123], v[172:173] op_sel_hi:[1,0]
	v_pk_mul_f32 v[192:193], v[116:117], v[172:173] op_sel_hi:[1,0]
	v_pk_mul_f32 v[194:195], v[118:119], v[172:173] op_sel_hi:[1,0]
	v_pk_mul_f32 v[196:197], v[108:109], v[174:175] op_sel_hi:[1,0]
	v_pk_mul_f32 v[198:199], v[110:111], v[174:175] op_sel_hi:[1,0]
	v_pk_mul_f32 v[200:201], v[100:101], v[174:175] op_sel_hi:[1,0]
	v_pk_mul_f32 v[202:203], v[102:103], v[174:175] op_sel_hi:[1,0]
	v_exp_f32_e32 v188, v188
	v_exp_f32_e32 v189, v189
	v_exp_f32_e32 v190, v190
	v_exp_f32_e32 v191, v191
	v_exp_f32_e32 v192, v192
	v_exp_f32_e32 v193, v193
	v_exp_f32_e32 v194, v194
	v_exp_f32_e32 v195, v195
	v_exp_f32_e32 v196, v196
	v_exp_f32_e32 v197, v197
	v_exp_f32_e32 v198, v198
	v_exp_f32_e32 v199, v199
	v_exp_f32_e32 v200, v200
	v_exp_f32_e32 v201, v201
	v_exp_f32_e32 v202, v202
	v_exp_f32_e32 v203, v203
	v_pk_fma_f32 v[188:189], v[188:189], v[172:173], v[172:173] op_sel:[0,1,1] op_sel_hi:[1,1,1]
	v_pk_fma_f32 v[190:191], v[190:191], v[172:173], v[172:173] op_sel:[0,1,1] op_sel_hi:[1,1,1]
	v_pk_fma_f32 v[192:193], v[192:193], v[172:173], v[172:173] op_sel:[0,1,1] op_sel_hi:[1,1,1]
	v_pk_fma_f32 v[194:195], v[194:195], v[172:173], v[172:173] op_sel:[0,1,1] op_sel_hi:[1,1,1]
	v_pk_fma_f32 v[196:197], v[196:197], v[174:175], v[174:175] op_sel:[0,1,1] op_sel_hi:[1,1,1]
	v_pk_fma_f32 v[198:199], v[198:199], v[174:175], v[174:175] op_sel:[0,1,1] op_sel_hi:[1,1,1]
	v_pk_fma_f32 v[200:201], v[200:201], v[174:175], v[174:175] op_sel:[0,1,1] op_sel_hi:[1,1,1]
; __device__ __forceinline__ unsigned cvt_pk_bf16(float lo, float hi) { unsigned r; asm volatile("v_cvt_pk_bf16_f32 %0, %1, %2" : "=v"(r) : "v"(lo), "v"(hi)); return r; }
; __device__ __forceinline__ unsigned silu_pk(f32x2 g, f32x2 u, float k1, float k2) {
;     const f32x2 t = g * k1; f32x2 ex; ex.x = __builtin_amdgcn_exp2f(t.x); ex.y = __builtin_amdgcn_exp2f(t.y);
;     const f32x2 d = ex + 1.0f; f32x2 r; r.x = __builtin_amdgcn_rcpf(d.x); r.y = __builtin_amdgcn_rcpf(d.y);
;     const f32x2 o = (g * u) * (r * k2);
;     return cvt_pk_bf16(o.x, o.y);
;     __device__ __forceinline__ void operator()(const f32x4 (&acc)[2][2][4][2], const Unit& u, int wr, int wc, int fr, int fq) const {
;     ...
;             for (int m = 0; m < 4; ++m) {
;                 const int row = row0 + ai * HALF + m * 16; const float rs = __builtin_amdgcn_rsqf(ssq[ai][m] * (1.0f / 1024.0f) + 1e-6f);
;                 const float k1 = -1.4426950408889634f * rs, k2 = rs * rs;
;                 u32x4 w;
; #pragma unroll
;                 for (int n = 0; n < 2; ++n) {
;                     const f32x4 gv = acc[ai][0][m][n], uv = acc[ai][1][m][n];
;                     const unsigned lo = silu_pk((f32x2){gv[0], gv[1]}, (f32x2){uv[0], uv[1]}, k1, k2), hi = silu_pk((f32x2){gv[2], gv[3]}, (f32x2){uv[2], uv[3]}, k1, k2);
;                     if (n == 0) { w.x = lo; w.y = hi; } else { w.z = lo; w.w = hi; }
;                 }
;                 *(u32x4*)(O + (size_t)row * ldc + col0) = w;
	v_pk_fma_f32 v[202:203], v[202:203], v[174:175], v[174:175] op_sel:[0,1,1] op_sel_hi:[1,1,1]
	v_rcp_f32_e32 v188, v188
	v_rcp_f32_e32 v189, v189
	v_rcp_f32_e32 v190, v190
	v_rcp_f32_e32 v191, v191
	v_rcp_f32_e32 v192, v192
	v_rcp_f32_e32 v193, v193
	v_rcp_f32_e32 v194, v194
	v_rcp_f32_e32 v195, v195
	v_rcp_f32_e32 v196, v196
	v_rcp_f32_e32 v197, v197
	v_rcp_f32_e32 v198, v198
	v_rcp_f32_e32 v199, v199
	v_rcp_f32_e32 v200, v200
	v_rcp_f32_e32 v201, v201
	v_rcp_f32_e32 v202, v202
	v_rcp_f32_e32 v203, v203
	v_pk_mul_f32 v[188:189], v[124:125], v[188:189]
	v_pk_mul_f32 v[190:191], v[126:127], v[190:191]
	v_pk_mul_f32 v[192:193], v[112:113], v[192:193]
	v_pk_mul_f32 v[194:195], v[114:115], v[194:195]
	v_pk_mul_f32 v[196:197], v[104:105], v[196:197]
	v_pk_mul_f32 v[198:199], v[106:107], v[198:199]
	v_pk_mul_f32 v[200:201], v[96:97], v[200:201]
	v_pk_mul_f32 v[202:203], v[98:99], v[202:203]
	v_cvt_pk_bf16_f32 v204, v188, v189
	v_cvt_pk_bf16_f32 v205, v190, v191
	v_cvt_pk_bf16_f32 v206, v192, v193
	v_cvt_pk_bf16_f32 v207, v194, v195
	v_cvt_pk_bf16_f32 v208, v196, v197
	v_cvt_pk_bf16_f32 v209, v198, v199
	v_cvt_pk_bf16_f32 v210, v200, v201
	v_cvt_pk_bf16_f32 v211, v202, v203
	global_store_dwordx4 v[220:221], v[204:207], off
	v_lshl_add_u64 v[220:221], v[220:221], 0, s[96:97]
	global_store_dwordx4 v[220:221], v[208:211], off
	v_lshl_add_u64 v[220:221], v[220:221], 0, s[96:97]
	v_pk_mul_f32 v[188:189], v[92:93], v[176:177] op_sel_hi:[1,0]
	v_pk_mul_f32 v[190:191], v[94:95], v[176:177] op_sel_hi:[1,0]
	v_pk_mul_f32 v[192:193], v[84:85], v[176:177] op_sel_hi:[1,0]
	v_pk_mul_f32 v[194:195], v[86:87], v[176:177] op_sel_hi:[1,0]
	v_pk_mul_f32 v[196:197], v[76:77], v[178:179] op_sel_hi:[1,0]
	v_pk_mul_f32 v[198:199], v[78:79], v[178:179] op_sel_hi:[1,0]
	v_pk_mul_f32 v[200:201], v[68:69], v[178:179] op_sel_hi:[1,0]
	v_pk_mul_f32 v[202:203], v[70:71], v[178:179] op_sel_hi:[1,0]
	v_exp_f32_e32 v188, v188
	v_exp_f32_e32 v189, v189
	v_exp_f32_e32 v190, v190
	v_exp_f32_e32 v191, v191
	v_exp_f32_e32 v192, v192
	v_exp_f32_e32 v193, v193
	v_exp_f32_e32 v194, v194
	v_exp_f32_e32 v195, v195
	v_exp_f32_e32 v196, v196
	v_exp_f32_e32 v197, v197
	v_exp_f32_e32 v198, v198
	v_exp_f32_e32 v199, v199
	v_exp_f32_e32 v200, v200
	v_exp_f32_e32 v201, v201
	v_exp_f32_e32 v202, v202
	v_exp_f32_e32 v203, v203
	v_pk_fma_f32 v[188:189], v[188:189], v[176:177], v[176:177] op_sel:[0,1,1] op_sel_hi:[1,1,1]
	v_pk_fma_f32 v[190:191], v[190:191], v[176:177], v[176:177] op_sel:[0,1,1] op_sel_hi:[1,1,1]
	v_pk_fma_f32 v[192:193], v[192:193], v[176:177], v[176:177] op_sel:[0,1,1] op_sel_hi:[1,1,1]
	v_pk_fma_f32 v[194:195], v[194:195], v[176:177], v[176:177] op_sel:[0,1,1] op_sel_hi:[1,1,1]
	v_pk_fma_f32 v[196:197], v[196:197], v[178:179], v[178:179] op_sel:[0,1,1] op_sel_hi:[1,1,1]
	v_pk_fma_f32 v[198:199], v[198:199], v[178:179], v[178:179] op_sel:[0,1,1] op_sel_hi:[1,1,1]
	v_pk_fma_f32 v[200:201], v[200:201], v[178:179], v[178:179] op_sel:[0,1,1] op_sel_hi:[1,1,1]
	v_pk_fma_f32 v[202:203], v[202:203], v[178:179], v[178:179] op_sel:[0,1,1] op_sel_hi:[1,1,1]
	v_rcp_f32_e32 v188, v188
	v_rcp_f32_e32 v189, v189
	v_rcp_f32_e32 v190, v190
	v_rcp_f32_e32 v191, v191
	v_rcp_f32_e32 v192, v192
	v_rcp_f32_e32 v193, v193
	v_rcp_f32_e32 v194, v194
	v_rcp_f32_e32 v195, v195
	v_rcp_f32_e32 v196, v196
	v_rcp_f32_e32 v197, v197
	v_rcp_f32_e32 v198, v198
	v_rcp_f32_e32 v199, v199
	v_rcp_f32_e32 v200, v200
	v_rcp_f32_e32 v201, v201
	v_rcp_f32_e32 v202, v202
	v_rcp_f32_e32 v203, v203
	v_pk_mul_f32 v[188:189], v[88:89], v[188:189]
	v_pk_mul_f32 v[190:191], v[90:91], v[190:191]
	v_pk_mul_f32 v[192:193], v[80:81], v[192:193]
	v_pk_mul_f32 v[194:195], v[82:83], v[194:195]
	v_pk_mul_f32 v[196:197], v[72:73], v[196:197]
	v_pk_mul_f32 v[198:199], v[74:75], v[198:199]
	v_pk_mul_f32 v[200:201], v[64:65], v[200:201]
	v_pk_mul_f32 v[202:203], v[66:67], v[202:203]
	v_cvt_pk_bf16_f32 v212, v188, v189
	v_cvt_pk_bf16_f32 v213, v190, v191
	v_cvt_pk_bf16_f32 v214, v192, v193
	v_cvt_pk_bf16_f32 v215, v194, v195
	v_cvt_pk_bf16_f32 v216, v196, v197
	v_cvt_pk_bf16_f32 v217, v198, v199
	v_cvt_pk_bf16_f32 v218, v200, v201
	v_cvt_pk_bf16_f32 v219, v202, v203
	global_store_dwordx4 v[220:221], v[212:215], off
	v_lshl_add_u64 v[220:221], v[220:221], 0, s[96:97]
	global_store_dwordx4 v[220:221], v[216:219], off
	v_lshl_add_u64 v[220:221], v[220:221], 0, s[98:99]
	v_pk_mul_f32 v[188:189], v[60:61], v[180:181] op_sel_hi:[1,0]
	v_pk_mul_f32 v[190:191], v[62:63], v[180:181] op_sel_hi:[1,0]
	v_pk_mul_f32 v[192:193], v[52:53], v[180:181] op_sel_hi:[1,0]
	v_pk_mul_f32 v[194:195], v[54:55], v[180:181] op_sel_hi:[1,0]
	v_pk_mul_f32 v[196:197], v[44:45], v[182:183] op_sel_hi:[1,0]
	v_pk_mul_f32 v[198:199], v[46:47], v[182:183] op_sel_hi:[1,0]
	v_pk_mul_f32 v[200:201], v[36:37], v[182:183] op_sel_hi:[1,0]
	v_pk_mul_f32 v[202:203], v[38:39], v[182:183] op_sel_hi:[1,0]
	v_exp_f32_e32 v188, v188
	v_exp_f32_e32 v189, v189
	v_exp_f32_e32 v190, v190
	v_exp_f32_e32 v191, v191
	v_exp_f32_e32 v192, v192
	v_exp_f32_e32 v193, v193
	v_exp_f32_e32 v194, v194
	v_exp_f32_e32 v195, v195
	v_exp_f32_e32 v196, v196
	v_exp_f32_e32 v197, v197
	v_exp_f32_e32 v198, v198
	v_exp_f32_e32 v199, v199
	v_exp_f32_e32 v200, v200
; __device__ __forceinline__ unsigned cvt_pk_bf16(float lo, float hi) { unsigned r; asm volatile("v_cvt_pk_bf16_f32 %0, %1, %2" : "=v"(r) : "v"(lo), "v"(hi)); return r; }
; __device__ __forceinline__ unsigned silu_pk(f32x2 g, f32x2 u, float k1, float k2) {
;     const f32x2 t = g * k1; f32x2 ex; ex.x = __builtin_amdgcn_exp2f(t.x); ex.y = __builtin_amdgcn_exp2f(t.y);
;     const f32x2 d = ex + 1.0f; f32x2 r; r.x = __builtin_amdgcn_rcpf(d.x); r.y = __builtin_amdgcn_rcpf(d.y);
;     const f32x2 o = (g * u) * (r * k2);
;     return cvt_pk_bf16(o.x, o.y);
;     __device__ __forceinline__ void operator()(const f32x4 (&acc)[2][2][4][2], const Unit& u, int wr, int wc, int fr, int fq) const {
;     ...
;             for (int m = 0; m < 4; ++m) {
;                 const int row = row0 + ai * HALF + m * 16; const float rs = __builtin_amdgcn_rsqf(ssq[ai][m] * (1.0f / 1024.0f) + 1e-6f);
;                 const float k1 = -1.4426950408889634f * rs, k2 = rs * rs;
;                 u32x4 w;
; #pragma unroll
;                 for (int n = 0; n < 2; ++n) {
;                     const f32x4 gv = acc[ai][0][m][n], uv = acc[ai][1][m][n];
;                     const unsigned lo = silu_pk((f32x2){gv[0], gv[1]}, (f32x2){uv[0], uv[1]}, k1, k2), hi = silu_pk((f32x2){gv[2], gv[3]}, (f32x2){uv[2], uv[3]}, k1, k2);
;                     if (n == 0) { w.x = lo; w.y = hi; } else { w.z = lo; w.w = hi; }
;                 }
;                 *(u32x4*)(O + (size_t)row * ldc + col0) = w;
	v_exp_f32_e32 v201, v201
	v_exp_f32_e32 v202, v202
	v_exp_f32_e32 v203, v203
	v_pk_fma_f32 v[188:189], v[188:189], v[180:181], v[180:181] op_sel:[0,1,1] op_sel_hi:[1,1,1]
	v_pk_fma_f32 v[190:191], v[190:191], v[180:181], v[180:181] op_sel:[0,1,1] op_sel_hi:[1,1,1]
	v_pk_fma_f32 v[192:193], v[192:193], v[180:181], v[180:181] op_sel:[0,1,1] op_sel_hi:[1,1,1]
	v_pk_fma_f32 v[194:195], v[194:195], v[180:181], v[180:181] op_sel:[0,1,1] op_sel_hi:[1,1,1]
	v_pk_fma_f32 v[196:197], v[196:197], v[182:183], v[182:183] op_sel:[0,1,1] op_sel_hi:[1,1,1]
	v_pk_fma_f32 v[198:199], v[198:199], v[182:183], v[182:183] op_sel:[0,1,1] op_sel_hi:[1,1,1]
	v_pk_fma_f32 v[200:201], v[200:201], v[182:183], v[182:183] op_sel:[0,1,1] op_sel_hi:[1,1,1]
	v_pk_fma_f32 v[202:203], v[202:203], v[182:183], v[182:183] op_sel:[0,1,1] op_sel_hi:[1,1,1]
	v_rcp_f32_e32 v188, v188
	v_rcp_f32_e32 v189, v189
	v_rcp_f32_e32 v190, v190
	v_rcp_f32_e32 v191, v191
	v_rcp_f32_e32 v192, v192
	v_rcp_f32_e32 v193, v193
	v_rcp_f32_e32 v194, v194
	v_rcp_f32_e32 v195, v195
	v_rcp_f32_e32 v196, v196
	v_rcp_f32_e32 v197, v197
	v_rcp_f32_e32 v198, v198
	v_rcp_f32_e32 v199, v199
	v_rcp_f32_e32 v200, v200
	v_rcp_f32_e32 v201, v201
	v_rcp_f32_e32 v202, v202
	v_rcp_f32_e32 v203, v203
	v_pk_mul_f32 v[188:189], v[56:57], v[188:189]
	v_pk_mul_f32 v[190:191], v[58:59], v[190:191]
	v_pk_mul_f32 v[192:193], v[48:49], v[192:193]
	v_pk_mul_f32 v[194:195], v[50:51], v[194:195]
	v_pk_mul_f32 v[196:197], v[40:41], v[196:197]
	v_pk_mul_f32 v[198:199], v[42:43], v[198:199]
	v_pk_mul_f32 v[200:201], v[32:33], v[200:201]
	v_pk_mul_f32 v[202:203], v[34:35], v[202:203]
	v_cvt_pk_bf16_f32 v204, v188, v189
	v_cvt_pk_bf16_f32 v205, v190, v191
	v_cvt_pk_bf16_f32 v206, v192, v193
	v_cvt_pk_bf16_f32 v207, v194, v195
	v_cvt_pk_bf16_f32 v208, v196, v197
	v_cvt_pk_bf16_f32 v209, v198, v199
	v_cvt_pk_bf16_f32 v210, v200, v201
	v_cvt_pk_bf16_f32 v211, v202, v203
	global_store_dwordx4 v[220:221], v[204:207], off
	v_lshl_add_u64 v[220:221], v[220:221], 0, s[96:97]
	global_store_dwordx4 v[220:221], v[208:211], off
	v_lshl_add_u64 v[220:221], v[220:221], 0, s[96:97]
	v_pk_mul_f32 v[188:189], v[28:29], v[184:185] op_sel_hi:[1,0]
	v_pk_mul_f32 v[190:191], v[30:31], v[184:185] op_sel_hi:[1,0]
	v_pk_mul_f32 v[192:193], v[20:21], v[184:185] op_sel_hi:[1,0]
	v_pk_mul_f32 v[194:195], v[22:23], v[184:185] op_sel_hi:[1,0]
	v_pk_mul_f32 v[196:197], v[12:13], v[186:187] op_sel_hi:[1,0]
	v_pk_mul_f32 v[198:199], v[14:15], v[186:187] op_sel_hi:[1,0]
	v_pk_mul_f32 v[200:201], v[4:5], v[186:187] op_sel_hi:[1,0]
	v_pk_mul_f32 v[202:203], v[6:7], v[186:187] op_sel_hi:[1,0]
	v_exp_f32_e32 v188, v188
	v_exp_f32_e32 v189, v189
	v_exp_f32_e32 v190, v190
	v_exp_f32_e32 v191, v191
	v_exp_f32_e32 v192, v192
	v_exp_f32_e32 v193, v193
	v_exp_f32_e32 v194, v194
	v_exp_f32_e32 v195, v195
	v_exp_f32_e32 v196, v196
	v_exp_f32_e32 v197, v197
	v_exp_f32_e32 v198, v198
	v_exp_f32_e32 v199, v199
	v_exp_f32_e32 v200, v200
	v_exp_f32_e32 v201, v201
	v_exp_f32_e32 v202, v202
	v_exp_f32_e32 v203, v203
	v_pk_fma_f32 v[188:189], v[188:189], v[184:185], v[184:185] op_sel:[0,1,1] op_sel_hi:[1,1,1]
	v_pk_fma_f32 v[190:191], v[190:191], v[184:185], v[184:185] op_sel:[0,1,1] op_sel_hi:[1,1,1]
	v_pk_fma_f32 v[192:193], v[192:193], v[184:185], v[184:185] op_sel:[0,1,1] op_sel_hi:[1,1,1]
	v_pk_fma_f32 v[194:195], v[194:195], v[184:185], v[184:185] op_sel:[0,1,1] op_sel_hi:[1,1,1]
	v_pk_fma_f32 v[196:197], v[196:197], v[186:187], v[186:187] op_sel:[0,1,1] op_sel_hi:[1,1,1]
	v_pk_fma_f32 v[198:199], v[198:199], v[186:187], v[186:187] op_sel:[0,1,1] op_sel_hi:[1,1,1]
	v_pk_fma_f32 v[200:201], v[200:201], v[186:187], v[186:187] op_sel:[0,1,1] op_sel_hi:[1,1,1]
	v_pk_fma_f32 v[202:203], v[202:203], v[186:187], v[186:187] op_sel:[0,1,1] op_sel_hi:[1,1,1]
	v_rcp_f32_e32 v188, v188
	v_rcp_f32_e32 v189, v189
	v_rcp_f32_e32 v190, v190
	v_rcp_f32_e32 v191, v191
	v_rcp_f32_e32 v192, v192
	v_rcp_f32_e32 v193, v193
	v_rcp_f32_e32 v194, v194
	v_rcp_f32_e32 v195, v195
	v_rcp_f32_e32 v196, v196
	v_rcp_f32_e32 v197, v197
	v_rcp_f32_e32 v198, v198
	v_rcp_f32_e32 v199, v199
	v_rcp_f32_e32 v200, v200
	v_rcp_f32_e32 v201, v201
	v_rcp_f32_e32 v202, v202
	v_rcp_f32_e32 v203, v203
	v_pk_mul_f32 v[188:189], v[24:25], v[188:189]
	v_pk_mul_f32 v[190:191], v[26:27], v[190:191]
	v_pk_mul_f32 v[192:193], v[16:17], v[192:193]
	v_pk_mul_f32 v[194:195], v[18:19], v[194:195]
	v_pk_mul_f32 v[196:197], v[8:9], v[196:197]
	v_pk_mul_f32 v[198:199], v[10:11], v[198:199]
	v_pk_mul_f32 v[200:201], v[0:1], v[200:201]
	v_pk_mul_f32 v[202:203], v[2:3], v[202:203]
	v_cvt_pk_bf16_f32 v212, v188, v189
	v_cvt_pk_bf16_f32 v213, v190, v191
	v_cvt_pk_bf16_f32 v214, v192, v193
	v_cvt_pk_bf16_f32 v215, v194, v195
	v_cvt_pk_bf16_f32 v216, v196, v197
	v_cvt_pk_bf16_f32 v217, v198, v199
	v_cvt_pk_bf16_f32 v218, v200, v201
	v_cvt_pk_bf16_f32 v219, v202, v203
	global_store_dwordx4 v[220:221], v[212:215], off
	v_lshl_add_u64 v[220:221], v[220:221], 0, s[96:97]
	global_store_dwordx4 v[220:221], v[216:219], off
	s_andn2_b64 vcc, exec, s[4:5]
	s_mov_b64 s[4:5], -1
	s_cbranch_vccnz .LBB0_228
	s_andn2_b64 vcc, exec, s[6:7]
	s_cbranch_vccnz .LBB0_227
	s_barrier
	s_branch .LBB0_227

; __device__ __forceinline__ unsigned cvt_pk_bf16(float lo, float hi) { unsigned r; asm volatile("v_cvt_pk_bf16_f32 %0, %1, %2" : "=v"(r) : "v"(lo), "v"(hi)); return r; }
; __device__ __forceinline__ float ld_agent(const rss_t* p) { return (float)__hip_atomic_load(p, __ATOMIC_RELAXED, __HIP_MEMORY_SCOPE_AGENT) * (1.0f / 16777216.0f); }
; __device__ __forceinline__ rss_t rss_fix(float ss) { return (rss_t)(ss * 16777216.0f); }
; __device__ __forceinline__ float rstd_of(const rss_t* rowss, int row) { return __builtin_amdgcn_rsqf(ld_agent(rowss + row) * (1.0f / 1024.0f) + 1e-6f); }
; __device__ __forceinline__ unsigned silu_pk(f32x2 g, f32x2 u, float k1, float k2) {
;     const f32x2 t = g * k1; f32x2 ex; ex.x = __builtin_amdgcn_exp2f(t.x); ex.y = __builtin_amdgcn_exp2f(t.y);
;     const f32x2 d = ex + 1.0f; f32x2 r; r.x = __builtin_amdgcn_rcpf(d.x); r.y = __builtin_amdgcn_rcpf(d.y);
;     const f32x2 o = (g * u) * (r * k2);
;     return cvt_pk_bf16(o.x, o.y);
;     __device__ __forceinline__ void operator()(const f32x4 (&acc)[2][2][4][2], const Unit& u, int wr, int wc, int fr, int fq) const {
;         const int row0 = u.pm * BM + wr * 64 + fr, col0 = u.pn * HALF + wc * 32 + 8 * fq;
;         float ssq[2][4];
; #pragma unroll
;         for (int ai = 0; ai < 2; ++ai)
; #pragma unroll
;             for (int m = 0; m < 4; ++m) ssq[ai][m] = ld_agent(rowss + row0 + ai * HALF + m * 16);
; #pragma unroll
;         for (int ai = 0; ai < 2; ++ai)
; #pragma unroll
;             for (int m = 0; m < 4; ++m) {
;                 const int row = row0 + ai * HALF + m * 16; const float rs = __builtin_amdgcn_rsqf(ssq[ai][m] * (1.0f / 1024.0f) + 1e-6f);
;                 const float k1 = -1.4426950408889634f * rs, k2 = rs * rs;
;                 u32x4 w;
; #pragma unroll
;                 for (int n = 0; n < 2; ++n) {
;                     const f32x4 gv = acc[ai][0][m][n], uv = acc[ai][1][m][n];
;                     const unsigned lo = silu_pk((f32x2){gv[0], gv[1]}, (f32x2){uv[0], uv[1]}, k1, k2), hi = silu_pk((f32x2){gv[2], gv[3]}, (f32x2){uv[2], uv[3]}, k1, k2);
;                     if (n == 0) { w.x = lo; w.y = hi; } else { w.z = lo; w.w = hi; }
;                 }
;                 *(u32x4*)(O + (size_t)row * ldc + col0) = w;
.LBB0_1197:
	v_lshl_add_u32 v144, s36, 8, v146
	v_ashrrev_i32_e32 v145, 31, v144
	v_lshl_add_u64 v[154:155], v[144:145], 3, s[12:13]
	global_load_dwordx2 v[156:157], v[154:155], off sc1
	global_load_dwordx2 v[158:159], v[154:155], off offset:128 sc1
	global_load_dwordx2 v[160:161], v[154:155], off offset:256 sc1
	global_load_dwordx2 v[162:163], v[154:155], off offset:384 sc1
	global_load_dwordx2 v[164:165], v[154:155], off offset:1024 sc1
	global_load_dwordx2 v[166:167], v[154:155], off offset:1152 sc1
	global_load_dwordx2 v[168:169], v[154:155], off offset:1280 sc1
	global_load_dwordx2 v[170:171], v[154:155], off offset:1408 sc1
	v_pk_mul_f32 v[124:125], v[120:121], v[124:125]
	v_pk_mul_f32 v[126:127], v[122:123], v[126:127]
	v_pk_mul_f32 v[112:113], v[116:117], v[112:113]
	v_pk_mul_f32 v[114:115], v[118:119], v[114:115]
	v_pk_mul_f32 v[104:105], v[108:109], v[104:105]
	v_pk_mul_f32 v[106:107], v[110:111], v[106:107]
	v_pk_mul_f32 v[96:97], v[100:101], v[96:97]
	v_pk_mul_f32 v[98:99], v[102:103], v[98:99]
	v_pk_mul_f32 v[88:89], v[92:93], v[88:89]
	v_pk_mul_f32 v[90:91], v[94:95], v[90:91]
	v_pk_mul_f32 v[80:81], v[84:85], v[80:81]
	v_pk_mul_f32 v[82:83], v[86:87], v[82:83]
	v_pk_mul_f32 v[72:73], v[76:77], v[72:73]
	v_pk_mul_f32 v[74:75], v[78:79], v[74:75]
	v_pk_mul_f32 v[64:65], v[68:69], v[64:65]
	v_pk_mul_f32 v[66:67], v[70:71], v[66:67]
	v_pk_mul_f32 v[56:57], v[60:61], v[56:57]
	v_pk_mul_f32 v[58:59], v[62:63], v[58:59]
	v_pk_mul_f32 v[48:49], v[52:53], v[48:49]
	v_pk_mul_f32 v[50:51], v[54:55], v[50:51]
	v_pk_mul_f32 v[40:41], v[44:45], v[40:41]
	v_pk_mul_f32 v[42:43], v[46:47], v[42:43]
	v_pk_mul_f32 v[32:33], v[36:37], v[32:33]
	v_pk_mul_f32 v[34:35], v[38:39], v[34:35]
	v_pk_mul_f32 v[24:25], v[28:29], v[24:25]
	v_pk_mul_f32 v[26:27], v[30:31], v[26:27]
	v_pk_mul_f32 v[16:17], v[20:21], v[16:17]
	v_pk_mul_f32 v[18:19], v[22:23], v[18:19]
	v_pk_mul_f32 v[8:9], v[12:13], v[8:9]
	v_pk_mul_f32 v[10:11], v[14:15], v[10:11]
	v_pk_mul_f32 v[0:1], v[4:5], v[0:1]
	v_pk_mul_f32 v[2:3], v[6:7], v[2:3]
	v_lshl_or_b32 v222, s63, 7, v148
	v_ashrrev_i32_e32 v223, 31, v222
	v_mov_b64_e32 v[224:225], s[8:9]
	v_lshlrev_b64 v[222:223], 1, v[222:223]
	v_mad_i64_i32 v[220:221], s[38:39], v144, s59, v[224:225]
	s_mov_b64 s[96:97], 0x16000
	s_mov_b64 s[98:99], 0x6e000
	v_lshl_add_u64 v[220:221], v[220:221], 0, v[222:223]
	s_waitcnt vmcnt(0)
	v_cvt_f32_u32_e32 v188, v157
	v_cvt_f32_u32_e32 v190, v159
	v_cvt_f32_u32_e32 v192, v161
	v_cvt_f32_u32_e32 v194, v163
	v_cvt_f32_u32_e32 v196, v165
	v_cvt_f32_u32_e32 v198, v167
	v_cvt_f32_u32_e32 v200, v169
	v_cvt_f32_u32_e32 v202, v171
	v_cvt_f32_u32_e32 v189, v156
	v_cvt_f32_u32_e32 v191, v158
	v_cvt_f32_u32_e32 v193, v160
	v_cvt_f32_u32_e32 v195, v162
	v_cvt_f32_u32_e32 v197, v164
	v_cvt_f32_u32_e32 v199, v166
	v_cvt_f32_u32_e32 v201, v168
	v_cvt_f32_u32_e32 v203, v170
	v_fmamk_f32 v188, v188, 0x4f800000, v189
	v_fmamk_f32 v190, v190, 0x4f800000, v191
	v_fmamk_f32 v192, v192, 0x4f800000, v193
	v_fmamk_f32 v194, v194, 0x4f800000, v195
	v_fmamk_f32 v196, v196, 0x4f800000, v197
	v_fmamk_f32 v198, v198, 0x4f800000, v199
	v_fmamk_f32 v200, v200, 0x4f800000, v201
	v_fmamk_f32 v202, v202, 0x4f800000, v203
	v_fmamk_f32 v173, v188, 0x2e800000, v152
	v_fmamk_f32 v175, v190, 0x2e800000, v152
	v_fmamk_f32 v177, v192, 0x2e800000, v152
	v_fmamk_f32 v179, v194, 0x2e800000, v152
	v_fmamk_f32 v181, v196, 0x2e800000, v152
	v_fmamk_f32 v183, v198, 0x2e800000, v152
	v_fmamk_f32 v185, v200, 0x2e800000, v152
	v_fmamk_f32 v187, v202, 0x2e800000, v152
	v_rsq_f32_e32 v172, v173
	v_rsq_f32_e32 v174, v175
	v_rsq_f32_e32 v176, v177
	v_rsq_f32_e32 v178, v179
	v_rsq_f32_e32 v180, v181
	v_rsq_f32_e32 v182, v183
	v_rsq_f32_e32 v184, v185
	v_rsq_f32_e32 v186, v187
	v_mul_f32_e32 v172, 0xbfb8aa3b, v172
	v_mul_f32_e32 v174, 0xbfb8aa3b, v174
	v_mul_f32_e32 v176, 0xbfb8aa3b, v176
	v_mul_f32_e32 v178, 0xbfb8aa3b, v178
	v_mul_f32_e32 v180, 0xbfb8aa3b, v180
	v_mul_f32_e32 v182, 0xbfb8aa3b, v182
	v_mul_f32_e32 v184, 0xbfb8aa3b, v184
	v_mul_f32_e32 v186, 0xbfb8aa3b, v186
	v_pk_mul_f32 v[188:189], v[120:121], v[172:173] op_sel_hi:[1,0]
	v_pk_mul_f32 v[190:191], v[122:123], v[172:173] op_sel_hi:[1,0]
	v_pk_mul_f32 v[192:193], v[116:117], v[172:173] op_sel_hi:[1,0]
	v_pk_mul_f32 v[194:195], v[118:119], v[172:173] op_sel_hi:[1,0]
	v_pk_mul_f32 v[196:197], v[108:109], v[174:175] op_sel_hi:[1,0]
	v_pk_mul_f32 v[198:199], v[110:111], v[174:175] op_sel_hi:[1,0]
	v_pk_mul_f32 v[200:201], v[100:101], v[174:175] op_sel_hi:[1,0]
	v_pk_mul_f32 v[202:203], v[102:103], v[174:175] op_sel_hi:[1,0]
	v_exp_f32_e32 v188, v188
	v_exp_f32_e32 v189, v189
	v_exp_f32_e32 v190, v190
	v_exp_f32_e32 v191, v191
	v_exp_f32_e32 v192, v192
	v_exp_f32_e32 v193, v193
	v_exp_f32_e32 v194, v194
	v_exp_f32_e32 v195, v195
	v_exp_f32_e32 v196, v196
	v_exp_f32_e32 v197, v197
	v_exp_f32_e32 v198, v198
	v_exp_f32_e32 v199, v199
	v_exp_f32_e32 v200, v200
	v_exp_f32_e32 v201, v201
	v_exp_f32_e32 v202, v202
	v_exp_f32_e32 v203, v203
	v_pk_fma_f32 v[188:189], v[188:189], v[172:173], v[172:173] op_sel:[0,1,1] op_sel_hi:[1,1,1]
	v_pk_fma_f32 v[190:191], v[190:191], v[172:173], v[172:173] op_sel:[0,1,1] op_sel_hi:[1,1,1]
	v_pk_fma_f32 v[192:193], v[192:193], v[172:173], v[172:173] op_sel:[0,1,1] op_sel_hi:[1,1,1]
	v_pk_fma_f32 v[194:195], v[194:195], v[172:173], v[172:173] op_sel:[0,1,1] op_sel_hi:[1,1,1]
	v_pk_fma_f32 v[196:197], v[196:197], v[174:175], v[174:175] op_sel:[0,1,1] op_sel_hi:[1,1,1]
	v_pk_fma_f32 v[198:199], v[198:199], v[174:175], v[174:175] op_sel:[0,1,1] op_sel_hi:[1,1,1]
	v_pk_fma_f32 v[200:201], v[200:201], v[174:175], v[174:175] op_sel:[0,1,1] op_sel_hi:[1,1,1]
; __device__ __forceinline__ unsigned cvt_pk_bf16(float lo, float hi) { unsigned r; asm volatile("v_cvt_pk_bf16_f32 %0, %1, %2" : "=v"(r) : "v"(lo), "v"(hi)); return r; }
; __device__ __forceinline__ unsigned silu_pk(f32x2 g, f32x2 u, float k1, float k2) {
;     const f32x2 t = g * k1; f32x2 ex; ex.x = __builtin_amdgcn_exp2f(t.x); ex.y = __builtin_amdgcn_exp2f(t.y);
;     const f32x2 d = ex + 1.0f; f32x2 r; r.x = __builtin_amdgcn_rcpf(d.x); r.y = __builtin_amdgcn_rcpf(d.y);
;     const f32x2 o = (g * u) * (r * k2);
;     return cvt_pk_bf16(o.x, o.y);
;     __device__ __forceinline__ void operator()(const f32x4 (&acc)[2][2][4][2], const Unit& u, int wr, int wc, int fr, int fq) const {
;     ...
;             for (int m = 0; m < 4; ++m) {
;                 const int row = row0 + ai * HALF + m * 16; const float rs = __builtin_amdgcn_rsqf(ssq[ai][m] * (1.0f / 1024.0f) + 1e-6f);
;                 const float k1 = -1.4426950408889634f * rs, k2 = rs * rs;
;                 u32x4 w;
; #pragma unroll
;                 for (int n = 0; n < 2; ++n) {
;                     const f32x4 gv = acc[ai][0][m][n], uv = acc[ai][1][m][n];
;                     const unsigned lo = silu_pk((f32x2){gv[0], gv[1]}, (f32x2){uv[0], uv[1]}, k1, k2), hi = silu_pk((f32x2){gv[2], gv[3]}, (f32x2){uv[2], uv[3]}, k1, k2);
;                     if (n == 0) { w.x = lo; w.y = hi; } else { w.z = lo; w.w = hi; }
;                 }
;                 *(u32x4*)(O + (size_t)row * ldc + col0) = w;
	v_pk_fma_f32 v[202:203], v[202:203], v[174:175], v[174:175] op_sel:[0,1,1] op_sel_hi:[1,1,1]
	v_rcp_f32_e32 v188, v188
	v_rcp_f32_e32 v189, v189
	v_rcp_f32_e32 v190, v190
	v_rcp_f32_e32 v191, v191
	v_rcp_f32_e32 v192, v192
	v_rcp_f32_e32 v193, v193
	v_rcp_f32_e32 v194, v194
	v_rcp_f32_e32 v195, v195
	v_rcp_f32_e32 v196, v196
	v_rcp_f32_e32 v197, v197
	v_rcp_f32_e32 v198, v198
	v_rcp_f32_e32 v199, v199
	v_rcp_f32_e32 v200, v200
	v_rcp_f32_e32 v201, v201
	v_rcp_f32_e32 v202, v202
	v_rcp_f32_e32 v203, v203
	v_pk_mul_f32 v[188:189], v[124:125], v[188:189]
	v_pk_mul_f32 v[190:191], v[126:127], v[190:191]
	v_pk_mul_f32 v[192:193], v[112:113], v[192:193]
	v_pk_mul_f32 v[194:195], v[114:115], v[194:195]
	v_pk_mul_f32 v[196:197], v[104:105], v[196:197]
	v_pk_mul_f32 v[198:199], v[106:107], v[198:199]
	v_pk_mul_f32 v[200:201], v[96:97], v[200:201]
	v_pk_mul_f32 v[202:203], v[98:99], v[202:203]
	v_cvt_pk_bf16_f32 v204, v188, v189
	v_cvt_pk_bf16_f32 v205, v190, v191
	v_cvt_pk_bf16_f32 v206, v192, v193
	v_cvt_pk_bf16_f32 v207, v194, v195
	v_cvt_pk_bf16_f32 v208, v196, v197
	v_cvt_pk_bf16_f32 v209, v198, v199
	v_cvt_pk_bf16_f32 v210, v200, v201
	v_cvt_pk_bf16_f32 v211, v202, v203
	global_store_dwordx4 v[220:221], v[204:207], off
	v_lshl_add_u64 v[220:221], v[220:221], 0, s[96:97]
	global_store_dwordx4 v[220:221], v[208:211], off
	v_lshl_add_u64 v[220:221], v[220:221], 0, s[96:97]
	v_pk_mul_f32 v[188:189], v[92:93], v[176:177] op_sel_hi:[1,0]
	v_pk_mul_f32 v[190:191], v[94:95], v[176:177] op_sel_hi:[1,0]
	v_pk_mul_f32 v[192:193], v[84:85], v[176:177] op_sel_hi:[1,0]
	v_pk_mul_f32 v[194:195], v[86:87], v[176:177] op_sel_hi:[1,0]
	v_pk_mul_f32 v[196:197], v[76:77], v[178:179] op_sel_hi:[1,0]
	v_pk_mul_f32 v[198:199], v[78:79], v[178:179] op_sel_hi:[1,0]
	v_pk_mul_f32 v[200:201], v[68:69], v[178:179] op_sel_hi:[1,0]
	v_pk_mul_f32 v[202:203], v[70:71], v[178:179] op_sel_hi:[1,0]
	v_exp_f32_e32 v188, v188
	v_exp_f32_e32 v189, v189
	v_exp_f32_e32 v190, v190
	v_exp_f32_e32 v191, v191
	v_exp_f32_e32 v192, v192
	v_exp_f32_e32 v193, v193
	v_exp_f32_e32 v194, v194
	v_exp_f32_e32 v195, v195
	v_exp_f32_e32 v196, v196
	v_exp_f32_e32 v197, v197
	v_exp_f32_e32 v198, v198
	v_exp_f32_e32 v199, v199
	v_exp_f32_e32 v200, v200
	v_exp_f32_e32 v201, v201
	v_exp_f32_e32 v202, v202
	v_exp_f32_e32 v203, v203
	v_pk_fma_f32 v[188:189], v[188:189], v[176:177], v[176:177] op_sel:[0,1,1] op_sel_hi:[1,1,1]
	v_pk_fma_f32 v[190:191], v[190:191], v[176:177], v[176:177] op_sel:[0,1,1] op_sel_hi:[1,1,1]
	v_pk_fma_f32 v[192:193], v[192:193], v[176:177], v[176:177] op_sel:[0,1,1] op_sel_hi:[1,1,1]
	v_pk_fma_f32 v[194:195], v[194:195], v[176:177], v[176:177] op_sel:[0,1,1] op_sel_hi:[1,1,1]
	v_pk_fma_f32 v[196:197], v[196:197], v[178:179], v[178:179] op_sel:[0,1,1] op_sel_hi:[1,1,1]
	v_pk_fma_f32 v[198:199], v[198:199], v[178:179], v[178:179] op_sel:[0,1,1] op_sel_hi:[1,1,1]
	v_pk_fma_f32 v[200:201], v[200:201], v[178:179], v[178:179] op_sel:[0,1,1] op_sel_hi:[1,1,1]
	v_pk_fma_f32 v[202:203], v[202:203], v[178:179], v[178:179] op_sel:[0,1,1] op_sel_hi:[1,1,1]
	v_rcp_f32_e32 v188, v188
	v_rcp_f32_e32 v189, v189
	v_rcp_f32_e32 v190, v190
	v_rcp_f32_e32 v191, v191
	v_rcp_f32_e32 v192, v192
	v_rcp_f32_e32 v193, v193
	v_rcp_f32_e32 v194, v194
	v_rcp_f32_e32 v195, v195
	v_rcp_f32_e32 v196, v196
	v_rcp_f32_e32 v197, v197
	v_rcp_f32_e32 v198, v198
	v_rcp_f32_e32 v199, v199
	v_rcp_f32_e32 v200, v200
	v_rcp_f32_e32 v201, v201
	v_rcp_f32_e32 v202, v202
	v_rcp_f32_e32 v203, v203
	v_pk_mul_f32 v[188:189], v[88:89], v[188:189]
	v_pk_mul_f32 v[190:191], v[90:91], v[190:191]
	v_pk_mul_f32 v[192:193], v[80:81], v[192:193]
	v_pk_mul_f32 v[194:195], v[82:83], v[194:195]
	v_pk_mul_f32 v[196:197], v[72:73], v[196:197]
	v_pk_mul_f32 v[198:199], v[74:75], v[198:199]
	v_pk_mul_f32 v[200:201], v[64:65], v[200:201]
	v_pk_mul_f32 v[202:203], v[66:67], v[202:203]
	v_cvt_pk_bf16_f32 v212, v188, v189
	v_cvt_pk_bf16_f32 v213, v190, v191
	v_cvt_pk_bf16_f32 v214, v192, v193
	v_cvt_pk_bf16_f32 v215, v194, v195
	v_cvt_pk_bf16_f32 v216, v196, v197
	v_cvt_pk_bf16_f32 v217, v198, v199
	v_cvt_pk_bf16_f32 v218, v200, v201
	v_cvt_pk_bf16_f32 v219, v202, v203
	global_store_dwordx4 v[220:221], v[212:215], off
	v_lshl_add_u64 v[220:221], v[220:221], 0, s[96:97]
	global_store_dwordx4 v[220:221], v[216:219], off
	v_lshl_add_u64 v[220:221], v[220:221], 0, s[98:99]
	v_pk_mul_f32 v[188:189], v[60:61], v[180:181] op_sel_hi:[1,0]
	v_pk_mul_f32 v[190:191], v[62:63], v[180:181] op_sel_hi:[1,0]
	v_pk_mul_f32 v[192:193], v[52:53], v[180:181] op_sel_hi:[1,0]
	v_pk_mul_f32 v[194:195], v[54:55], v[180:181] op_sel_hi:[1,0]
	v_pk_mul_f32 v[196:197], v[44:45], v[182:183] op_sel_hi:[1,0]
	v_pk_mul_f32 v[198:199], v[46:47], v[182:183] op_sel_hi:[1,0]
	v_pk_mul_f32 v[200:201], v[36:37], v[182:183] op_sel_hi:[1,0]
	v_pk_mul_f32 v[202:203], v[38:39], v[182:183] op_sel_hi:[1,0]
	v_exp_f32_e32 v188, v188
	v_exp_f32_e32 v189, v189
	v_exp_f32_e32 v190, v190
	v_exp_f32_e32 v191, v191
	v_exp_f32_e32 v192, v192
	v_exp_f32_e32 v193, v193
	v_exp_f32_e32 v194, v194
	v_exp_f32_e32 v195, v195
	v_exp_f32_e32 v196, v196
	v_exp_f32_e32 v197, v197
	v_exp_f32_e32 v198, v198
	v_exp_f32_e32 v199, v199
	v_exp_f32_e32 v200, v200
; __device__ __forceinline__ unsigned cvt_pk_bf16(float lo, float hi) { unsigned r; asm volatile("v_cvt_pk_bf16_f32 %0, %1, %2" : "=v"(r) : "v"(lo), "v"(hi)); return r; }
; __device__ __forceinline__ unsigned silu_pk(f32x2 g, f32x2 u, float k1, float k2) {
;     const f32x2 t = g * k1; f32x2 ex; ex.x = __builtin_amdgcn_exp2f(t.x); ex.y = __builtin_amdgcn_exp2f(t.y);
;     const f32x2 d = ex + 1.0f; f32x2 r; r.x = __builtin_amdgcn_rcpf(d.x); r.y = __builtin_amdgcn_rcpf(d.y);
;     const f32x2 o = (g * u) * (r * k2);
;     return cvt_pk_bf16(o.x, o.y);
;     __device__ __forceinline__ void operator()(const f32x4 (&acc)[2][2][4][2], const Unit& u, int wr, int wc, int fr, int fq) const {
;     ...
;             for (int m = 0; m < 4; ++m) {
;                 const int row = row0 + ai * HALF + m * 16; const float rs = __builtin_amdgcn_rsqf(ssq[ai][m] * (1.0f / 1024.0f) + 1e-6f);
;                 const float k1 = -1.4426950408889634f * rs, k2 = rs * rs;
;                 u32x4 w;
; #pragma unroll
;                 for (int n = 0; n < 2; ++n) {
;                     const f32x4 gv = acc[ai][0][m][n], uv = acc[ai][1][m][n];
;                     const unsigned lo = silu_pk((f32x2){gv[0], gv[1]}, (f32x2){uv[0], uv[1]}, k1, k2), hi = silu_pk((f32x2){gv[2], gv[3]}, (f32x2){uv[2], uv[3]}, k1, k2);
;                     if (n == 0) { w.x = lo; w.y = hi; } else { w.z = lo; w.w = hi; }
;                 }
;                 *(u32x4*)(O + (size_t)row * ldc + col0) = w;
	v_exp_f32_e32 v201, v201
	v_exp_f32_e32 v202, v202
	v_exp_f32_e32 v203, v203
	v_pk_fma_f32 v[188:189], v[188:189], v[180:181], v[180:181] op_sel:[0,1,1] op_sel_hi:[1,1,1]
	v_pk_fma_f32 v[190:191], v[190:191], v[180:181], v[180:181] op_sel:[0,1,1] op_sel_hi:[1,1,1]
	v_pk_fma_f32 v[192:193], v[192:193], v[180:181], v[180:181] op_sel:[0,1,1] op_sel_hi:[1,1,1]
	v_pk_fma_f32 v[194:195], v[194:195], v[180:181], v[180:181] op_sel:[0,1,1] op_sel_hi:[1,1,1]
	v_pk_fma_f32 v[196:197], v[196:197], v[182:183], v[182:183] op_sel:[0,1,1] op_sel_hi:[1,1,1]
	v_pk_fma_f32 v[198:199], v[198:199], v[182:183], v[182:183] op_sel:[0,1,1] op_sel_hi:[1,1,1]
	v_pk_fma_f32 v[200:201], v[200:201], v[182:183], v[182:183] op_sel:[0,1,1] op_sel_hi:[1,1,1]
	v_pk_fma_f32 v[202:203], v[202:203], v[182:183], v[182:183] op_sel:[0,1,1] op_sel_hi:[1,1,1]
	v_rcp_f32_e32 v188, v188
	v_rcp_f32_e32 v189, v189
	v_rcp_f32_e32 v190, v190
	v_rcp_f32_e32 v191, v191
	v_rcp_f32_e32 v192, v192
	v_rcp_f32_e32 v193, v193
	v_rcp_f32_e32 v194, v194
	v_rcp_f32_e32 v195, v195
	v_rcp_f32_e32 v196, v196
	v_rcp_f32_e32 v197, v197
	v_rcp_f32_e32 v198, v198
	v_rcp_f32_e32 v199, v199
	v_rcp_f32_e32 v200, v200
	v_rcp_f32_e32 v201, v201
	v_rcp_f32_e32 v202, v202
	v_rcp_f32_e32 v203, v203
	v_pk_mul_f32 v[188:189], v[56:57], v[188:189]
	v_pk_mul_f32 v[190:191], v[58:59], v[190:191]
	v_pk_mul_f32 v[192:193], v[48:49], v[192:193]
	v_pk_mul_f32 v[194:195], v[50:51], v[194:195]
	v_pk_mul_f32 v[196:197], v[40:41], v[196:197]
	v_pk_mul_f32 v[198:199], v[42:43], v[198:199]
	v_pk_mul_f32 v[200:201], v[32:33], v[200:201]
	v_pk_mul_f32 v[202:203], v[34:35], v[202:203]
	v_cvt_pk_bf16_f32 v204, v188, v189
	v_cvt_pk_bf16_f32 v205, v190, v191
	v_cvt_pk_bf16_f32 v206, v192, v193
	v_cvt_pk_bf16_f32 v207, v194, v195
	v_cvt_pk_bf16_f32 v208, v196, v197
	v_cvt_pk_bf16_f32 v209, v198, v199
	v_cvt_pk_bf16_f32 v210, v200, v201
	v_cvt_pk_bf16_f32 v211, v202, v203
	global_store_dwordx4 v[220:221], v[204:207], off
	v_lshl_add_u64 v[220:221], v[220:221], 0, s[96:97]
	global_store_dwordx4 v[220:221], v[208:211], off
	v_lshl_add_u64 v[220:221], v[220:221], 0, s[96:97]
	v_pk_mul_f32 v[188:189], v[28:29], v[184:185] op_sel_hi:[1,0]
	v_pk_mul_f32 v[190:191], v[30:31], v[184:185] op_sel_hi:[1,0]
	v_pk_mul_f32 v[192:193], v[20:21], v[184:185] op_sel_hi:[1,0]
	v_pk_mul_f32 v[194:195], v[22:23], v[184:185] op_sel_hi:[1,0]
	v_pk_mul_f32 v[196:197], v[12:13], v[186:187] op_sel_hi:[1,0]
	v_pk_mul_f32 v[198:199], v[14:15], v[186:187] op_sel_hi:[1,0]
	v_pk_mul_f32 v[200:201], v[4:5], v[186:187] op_sel_hi:[1,0]
	v_pk_mul_f32 v[202:203], v[6:7], v[186:187] op_sel_hi:[1,0]
	v_exp_f32_e32 v188, v188
	v_exp_f32_e32 v189, v189
	v_exp_f32_e32 v190, v190
	v_exp_f32_e32 v191, v191
	v_exp_f32_e32 v192, v192
	v_exp_f32_e32 v193, v193
	v_exp_f32_e32 v194, v194
	v_exp_f32_e32 v195, v195
	v_exp_f32_e32 v196, v196
	v_exp_f32_e32 v197, v197
	v_exp_f32_e32 v198, v198
	v_exp_f32_e32 v199, v199
	v_exp_f32_e32 v200, v200
	v_exp_f32_e32 v201, v201
	v_exp_f32_e32 v202, v202
	v_exp_f32_e32 v203, v203
	v_pk_fma_f32 v[188:189], v[188:189], v[184:185], v[184:185] op_sel:[0,1,1] op_sel_hi:[1,1,1]
	v_pk_fma_f32 v[190:191], v[190:191], v[184:185], v[184:185] op_sel:[0,1,1] op_sel_hi:[1,1,1]
	v_pk_fma_f32 v[192:193], v[192:193], v[184:185], v[184:185] op_sel:[0,1,1] op_sel_hi:[1,1,1]
	v_pk_fma_f32 v[194:195], v[194:195], v[184:185], v[184:185] op_sel:[0,1,1] op_sel_hi:[1,1,1]
	v_pk_fma_f32 v[196:197], v[196:197], v[186:187], v[186:187] op_sel:[0,1,1] op_sel_hi:[1,1,1]
	v_pk_fma_f32 v[198:199], v[198:199], v[186:187], v[186:187] op_sel:[0,1,1] op_sel_hi:[1,1,1]
	v_pk_fma_f32 v[200:201], v[200:201], v[186:187], v[186:187] op_sel:[0,1,1] op_sel_hi:[1,1,1]
	v_pk_fma_f32 v[202:203], v[202:203], v[186:187], v[186:187] op_sel:[0,1,1] op_sel_hi:[1,1,1]
	v_rcp_f32_e32 v188, v188
	v_rcp_f32_e32 v189, v189
	v_rcp_f32_e32 v190, v190
	v_rcp_f32_e32 v191, v191
	v_rcp_f32_e32 v192, v192
	v_rcp_f32_e32 v193, v193
	v_rcp_f32_e32 v194, v194
	v_rcp_f32_e32 v195, v195
	v_rcp_f32_e32 v196, v196
	v_rcp_f32_e32 v197, v197
	v_rcp_f32_e32 v198, v198
	v_rcp_f32_e32 v199, v199
	v_rcp_f32_e32 v200, v200
	v_rcp_f32_e32 v201, v201
	v_rcp_f32_e32 v202, v202
	v_rcp_f32_e32 v203, v203
	v_pk_mul_f32 v[188:189], v[24:25], v[188:189]
	v_pk_mul_f32 v[190:191], v[26:27], v[190:191]
	v_pk_mul_f32 v[192:193], v[16:17], v[192:193]
	v_pk_mul_f32 v[194:195], v[18:19], v[194:195]
	v_pk_mul_f32 v[196:197], v[8:9], v[196:197]
	v_pk_mul_f32 v[198:199], v[10:11], v[198:199]
	v_pk_mul_f32 v[200:201], v[0:1], v[200:201]
	v_pk_mul_f32 v[202:203], v[2:3], v[202:203]
	v_cvt_pk_bf16_f32 v212, v188, v189
	v_cvt_pk_bf16_f32 v213, v190, v191
	v_cvt_pk_bf16_f32 v214, v192, v193
	v_cvt_pk_bf16_f32 v215, v194, v195
	v_cvt_pk_bf16_f32 v216, v196, v197
	v_cvt_pk_bf16_f32 v217, v198, v199
	v_cvt_pk_bf16_f32 v218, v200, v201
	v_cvt_pk_bf16_f32 v219, v202, v203
	global_store_dwordx4 v[220:221], v[212:215], off
	v_lshl_add_u64 v[220:221], v[220:221], 0, s[96:97]
	global_store_dwordx4 v[220:221], v[216:219], off
	s_andn2_b64 vcc, exec, s[4:5]
	s_mov_b64 s[4:5], -1
	s_cbranch_vccnz .LBB0_1190
	s_andn2_b64 vcc, exec, s[6:7]
	s_cbranch_vccnz .LBB0_1189
	s_barrier
	s_branch .LBB0_1189

; __global__ void __launch_bounds__(512, 2) fwd(Args a) {
	.amdhsa_kernel _Z3fwd4Args
		.amdhsa_group_segment_fixed_size 0
		.amdhsa_private_segment_fixed_size 0
		.amdhsa_kernarg_size 488
		.amdhsa_user_sgpr_count 2
		.amdhsa_user_sgpr_dispatch_ptr 0
		.amdhsa_user_sgpr_queue_ptr 0
		.amdhsa_user_sgpr_kernarg_segment_ptr 1
		.amdhsa_user_sgpr_dispatch_id 0
		.amdhsa_user_sgpr_kernarg_preload_length 0
		.amdhsa_user_sgpr_kernarg_preload_offset 0
		.amdhsa_user_sgpr_private_segment_size 0
		.amdhsa_uses_dynamic_stack 0
		.amdhsa_enable_private_segment 0
		.amdhsa_system_sgpr_workgroup_id_x 1
		.amdhsa_system_sgpr_workgroup_id_y 0
		.amdhsa_system_sgpr_workgroup_id_z 0
		.amdhsa_system_sgpr_workgroup_info 0
		.amdhsa_system_vgpr_workitem_id 2
		.amdhsa_next_free_vgpr 256
		.amdhsa_next_free_sgpr 100
		.amdhsa_accum_offset 256
		.amdhsa_reserve_vcc 1
		.amdhsa_float_round_mode_32 0
		.amdhsa_float_round_mode_16_64 0
		.amdhsa_float_denorm_mode_32 3
		.amdhsa_float_denorm_mode_16_64 3
		.amdhsa_dx10_clamp 1
		.amdhsa_ieee_mode 1
		.amdhsa_fp16_overflow 0
		.amdhsa_tg_split 0
		.amdhsa_exception_fp_ieee_invalid_op 0
		.amdhsa_exception_fp_denorm_src 0
		.amdhsa_exception_fp_ieee_div_zero 0
		.amdhsa_exception_fp_ieee_overflow 0
		.amdhsa_exception_fp_ieee_underflow 0
		.amdhsa_exception_fp_ieee_inexact 0
		.amdhsa_exception_int_div_zero 0
	.end_amdhsa_kernel

; __global__ void __launch_bounds__(512, 2) fwd(Args a) {
amdhsa.kernels:
  - .agpr_count:     0
    .args:
      - .offset:         0
        .size:           232
        .value_kind:     by_value
      - .offset:         232
        .size:           4
        .value_kind:     hidden_block_count_x
      - .offset:         236
        .size:           4
        .value_kind:     hidden_block_count_y
      - .offset:         240
        .size:           4
        .value_kind:     hidden_block_count_z
      - .offset:         244
        .size:           2
        .value_kind:     hidden_group_size_x
      - .offset:         246
        .size:           2
        .value_kind:     hidden_group_size_y
      - .offset:         248
        .size:           2
        .value_kind:     hidden_group_size_z
      - .offset:         250
        .size:           2
        .value_kind:     hidden_remainder_x
      - .offset:         252
        .size:           2
        .value_kind:     hidden_remainder_y
      - .offset:         254
        .size:           2
        .value_kind:     hidden_remainder_z
      - .offset:         272
        .size:           8
        .value_kind:     hidden_global_offset_x
      - .offset:         280
        .size:           8
        .value_kind:     hidden_global_offset_y
      - .offset:         288
        .size:           8
        .value_kind:     hidden_global_offset_z
      - .offset:         296
        .size:           2
        .value_kind:     hidden_grid_dims
      - .offset:         320
        .size:           8
        .value_kind:     hidden_multigrid_sync_arg
      - .offset:         352
        .size:           4
        .value_kind:     hidden_dynamic_lds_size
    .group_segment_fixed_size: 0
    .kernarg_segment_align: 8
    .kernarg_segment_size: 488
    .language:       OpenCL C
    .language_version:
      - 2
      - 0
    .max_flat_workgroup_size: 512
    .name:           _Z3fwd4Args
    .private_segment_fixed_size: 0
    .sgpr_count:     106
    .sgpr_spill_count: 0
    .symbol:         _Z3fwd4Args.kd
    .uniform_work_group_size: 1
    .uses_dynamic_stack: false
    .vgpr_count:     256
    .vgpr_spill_count: 0
    .wavefront_size: 64
